# v21: v18 + every 32-MFMA run of the three GEMM k-loops starts on an 8-byte boundary (one s_nop 0 pad where needed)
# speedup vs baseline: 1.0051x; 1.0051x over previous
.LBB0_155:
	s_ashr_i32 s23, s22, 31
	s_lshl_b64 s[8:9], s[22:23], 19
	s_add_u32 s24, s30, s8
	s_addc_u32 s25, s31, s9
	s_and_b64 s[8:9], s[4:5], exec
	s_cselect_b32 s3, s25, s1
	s_cselect_b32 s23, s24, s0
	s_ashr_i32 s21, s20, 31
	s_lshl_b64 s[8:9], s[20:21], 19
	s_add_u32 s26, s34, s8
	s_addc_u32 s27, s35, s9
	s_and_b64 s[8:9], s[4:5], exec
	s_cselect_b32 s21, s27, s7
	s_cselect_b32 s28, s26, s6
	s_add_u32 s0, s0, 0x40080
	s_addc_u32 s1, s1, 0
	s_add_u32 s29, s6, 0x100
	s_addc_u32 s42, s7, 0
	s_mov_b32 s49, -2
	s_add_u32 s6, s0, 0xfffc0080
	s_addc_u32 s7, s1, -1
	s_add_i32 s50, 16, 0x10000
	s_cmp_eq_u32 s49, 12
	s_cselect_b32 s9, s3, s7
	s_cselect_b32 s8, s23, s6
	v_add_u32_e32 v151, s50, v176
	s_cselect_b32 s7, s21, s42
	s_cselect_b32 s6, s28, s29
	s_add_i32 s52, 16, 0x14000
	ds_read_b128 v[132:135], v151
	ds_read_b128 v[152:155], v151 offset:1024
	ds_read_b128 v[156:159], v151 offset:2048
	ds_read_b128 v[160:163], v151 offset:3072
	v_add_u32_e32 v151, s52, v176
	ds_read_b128 v[164:167], v151
	ds_read_b128 v[168:171], v151 offset:1024
	ds_read_b128 v[172:175], v151 offset:2048
	ds_read_b128 v[180:183], v151 offset:3072
	v_lshl_add_u64 v[216:217], s[0:1], 0, v[146:147]
	s_add_i32 m0, s37, 0xc000
	ds_read_b128 v[184:187], v178
	ds_read_b128 v[188:191], v178 offset:1024
	ds_read_b128 v[192:195], v178 offset:2048
	ds_read_b128 v[196:199], v178 offset:3072
	ds_read_b128 v[200:203], v178 offset:4096
	ds_read_b128 v[204:207], v178 offset:5120
	ds_read_b128 v[208:211], v178 offset:6144
	ds_read_b128 v[212:215], v178 offset:7168
	global_load_lds_dwordx4 v[216:217], off
	v_lshl_add_u64 v[216:217], s[0:1], 0, v[148:149]
	s_add_i32 m0, s37, 0xe000
	s_nop 0
	global_load_lds_dwordx4 v[216:217], off
	s_waitcnt vmcnt(8)
	s_waitcnt lgkmcnt(0)
	s_barrier
	s_setprio 1
	s_waitcnt lgkmcnt(0)
	s_nop 0
	v_mfma_f32_16x16x32_bf16 v[128:131], v[132:135], v[184:187], 0
	v_mfma_f32_16x16x32_bf16 v[124:127], v[156:159], v[184:187], 0
	v_mfma_f32_16x16x32_bf16 v[112:115], v[132:135], v[192:195], 0
	v_mfma_f32_16x16x32_bf16 v[108:111], v[156:159], v[192:195], 0
	v_mfma_f32_16x16x32_bf16 v[96:99], v[132:135], v[200:203], 0
	v_mfma_f32_16x16x32_bf16 v[92:95], v[156:159], v[200:203], 0
	v_mfma_f32_16x16x32_bf16 v[80:83], v[132:135], v[208:211], 0
	v_mfma_f32_16x16x32_bf16 v[76:79], v[156:159], v[208:211], 0
	v_mfma_f32_16x16x32_bf16 v[128:131], v[152:155], v[188:191], v[128:131]
	v_mfma_f32_16x16x32_bf16 v[124:127], v[160:163], v[188:191], v[124:127]
	v_mfma_f32_16x16x32_bf16 v[112:115], v[152:155], v[196:199], v[112:115]
	v_mfma_f32_16x16x32_bf16 v[108:111], v[160:163], v[196:199], v[108:111]
	v_mfma_f32_16x16x32_bf16 v[96:99], v[152:155], v[204:207], v[96:99]
	v_mfma_f32_16x16x32_bf16 v[92:95], v[160:163], v[204:207], v[92:95]
	v_mfma_f32_16x16x32_bf16 v[80:83], v[152:155], v[212:215], v[80:83]
	v_mfma_f32_16x16x32_bf16 v[76:79], v[160:163], v[212:215], v[76:79]
	s_setprio 0
	s_setprio 1
	v_mfma_f32_16x16x32_bf16 v[120:123], v[164:167], v[184:187], 0
	v_mfma_f32_16x16x32_bf16 v[116:119], v[172:175], v[184:187], 0
	v_mfma_f32_16x16x32_bf16 v[104:107], v[164:167], v[192:195], 0
	v_mfma_f32_16x16x32_bf16 v[100:103], v[172:175], v[192:195], 0
	v_mfma_f32_16x16x32_bf16 v[88:91], v[164:167], v[200:203], 0
	v_mfma_f32_16x16x32_bf16 v[84:87], v[172:175], v[200:203], 0
	v_mfma_f32_16x16x32_bf16 v[72:75], v[164:167], v[208:211], 0
	v_mfma_f32_16x16x32_bf16 v[68:71], v[172:175], v[208:211], 0
	v_mfma_f32_16x16x32_bf16 v[120:123], v[168:171], v[188:191], v[120:123]
	v_mfma_f32_16x16x32_bf16 v[116:119], v[180:183], v[188:191], v[116:119]
	v_mfma_f32_16x16x32_bf16 v[104:107], v[168:171], v[196:199], v[104:107]
	v_mfma_f32_16x16x32_bf16 v[100:103], v[180:183], v[196:199], v[100:103]
	v_mfma_f32_16x16x32_bf16 v[88:91], v[168:171], v[204:207], v[88:91]
	v_mfma_f32_16x16x32_bf16 v[84:87], v[180:183], v[204:207], v[84:87]
	v_mfma_f32_16x16x32_bf16 v[72:75], v[168:171], v[212:215], v[72:75]
	v_mfma_f32_16x16x32_bf16 v[68:71], v[180:183], v[212:215], v[68:71]
	s_setprio 0
	s_barrier
	s_add_i32 s50, s50, s36
	v_lshl_add_u64 v[216:217], s[6:7], 0, v[138:139]
	s_mov_b32 m0, s50
	ds_read_b128 v[184:187], v178 offset:16384
	ds_read_b128 v[188:191], v178 offset:17408
	ds_read_b128 v[192:195], v178 offset:18432
	ds_read_b128 v[196:199], v178 offset:19456
	ds_read_b128 v[200:203], v178 offset:20480
	ds_read_b128 v[204:207], v178 offset:21504
	ds_read_b128 v[208:211], v178 offset:22528
	ds_read_b128 v[212:215], v178 offset:23552
	global_load_lds_dwordx4 v[216:217], off
	s_add_i32 m0, s50, 0x2000
	s_add_u32 s50, s6, 0x40000
	v_lshl_add_u64 v[218:219], s[6:7], 0, v[0:1]
	s_addc_u32 s51, s7, 0
	s_add_i32 s52, s52, s36
	global_load_lds_dwordx4 v[218:219], off
	v_lshl_add_u64 v[220:221], s[50:51], 0, v[138:139]
	s_mov_b32 m0, s52
	v_lshl_add_u64 v[224:225], s[8:9], 0, v[136:137]
	global_load_lds_dwordx4 v[220:221], off
	v_lshl_add_u64 v[220:221], s[50:51], 0, v[0:1]
	s_add_i32 m0, s52, 0x2000
	s_nop 0
	global_load_lds_dwordx4 v[220:221], off
	v_lshl_add_u64 v[220:221], s[8:9], 0, v[140:141]
	s_waitcnt vmcnt(6)
	s_waitcnt lgkmcnt(0)
	s_barrier
	s_setprio 1
	s_waitcnt lgkmcnt(0)
	s_nop 0
	v_mfma_f32_16x16x32_bf16 v[64:67], v[132:135], v[184:187], 0
	v_mfma_f32_16x16x32_bf16 v[60:63], v[156:159], v[184:187], 0
	v_mfma_f32_16x16x32_bf16 v[48:51], v[132:135], v[192:195], 0
	v_mfma_f32_16x16x32_bf16 v[44:47], v[156:159], v[192:195], 0
	v_mfma_f32_16x16x32_bf16 v[32:35], v[132:135], v[200:203], 0
	v_mfma_f32_16x16x32_bf16 v[28:31], v[156:159], v[200:203], 0
	v_mfma_f32_16x16x32_bf16 v[16:19], v[132:135], v[208:211], 0
	v_mfma_f32_16x16x32_bf16 v[12:15], v[156:159], v[208:211], 0
	v_mfma_f32_16x16x32_bf16 v[64:67], v[152:155], v[188:191], v[64:67]
	v_mfma_f32_16x16x32_bf16 v[60:63], v[160:163], v[188:191], v[60:63]
	v_mfma_f32_16x16x32_bf16 v[48:51], v[152:155], v[196:199], v[48:51]
	v_mfma_f32_16x16x32_bf16 v[44:47], v[160:163], v[196:199], v[44:47]
	v_mfma_f32_16x16x32_bf16 v[32:35], v[152:155], v[204:207], v[32:35]
	v_mfma_f32_16x16x32_bf16 v[28:31], v[160:163], v[204:207], v[28:31]
	v_mfma_f32_16x16x32_bf16 v[16:19], v[152:155], v[212:215], v[16:19]
	v_mfma_f32_16x16x32_bf16 v[12:15], v[160:163], v[212:215], v[12:15]
	s_setprio 0
	s_setprio 1
	v_mfma_f32_16x16x32_bf16 v[56:59], v[164:167], v[184:187], 0
	v_mfma_f32_16x16x32_bf16 v[52:55], v[172:175], v[184:187], 0
	v_mfma_f32_16x16x32_bf16 v[40:43], v[164:167], v[192:195], 0
	v_mfma_f32_16x16x32_bf16 v[36:39], v[172:175], v[192:195], 0
	v_mfma_f32_16x16x32_bf16 v[24:27], v[164:167], v[200:203], 0
	v_mfma_f32_16x16x32_bf16 v[20:23], v[172:175], v[200:203], 0
	v_mfma_f32_16x16x32_bf16 v[8:11], v[164:167], v[208:211], 0
	v_mfma_f32_16x16x32_bf16 v[4:7], v[172:175], v[208:211], 0
	v_mfma_f32_16x16x32_bf16 v[56:59], v[168:171], v[188:191], v[56:59]
	v_mfma_f32_16x16x32_bf16 v[52:55], v[180:183], v[188:191], v[52:55]
	v_mfma_f32_16x16x32_bf16 v[40:43], v[168:171], v[196:199], v[40:43]
	v_mfma_f32_16x16x32_bf16 v[36:39], v[180:183], v[196:199], v[36:39]
	v_mfma_f32_16x16x32_bf16 v[24:27], v[168:171], v[204:207], v[24:27]
	v_mfma_f32_16x16x32_bf16 v[20:23], v[180:183], v[204:207], v[20:23]
	v_mfma_f32_16x16x32_bf16 v[8:11], v[168:171], v[212:215], v[8:11]
	v_mfma_f32_16x16x32_bf16 v[4:7], v[180:183], v[212:215], v[4:7]
	s_setprio 0
	s_barrier
	s_branch .Lb1_ph3
.LBB0_156:
	s_add_u32 s6, s0, 0xfffc0080
	s_addc_u32 s7, s1, -1
	s_add_i32 s50, 16, 0x10000
	s_cmp_eq_u32 s49, 12
	s_cselect_b32 s9, s3, s7
	s_cselect_b32 s8, s23, s6
	v_add_u32_e32 v151, s50, v176
	s_cselect_b32 s7, s21, s42
	s_cselect_b32 s6, s28, s29
	s_add_i32 s52, 16, 0x14000
	ds_read_b128 v[132:135], v151
	ds_read_b128 v[152:155], v151 offset:1024
	ds_read_b128 v[156:159], v151 offset:2048
	ds_read_b128 v[160:163], v151 offset:3072
	v_add_u32_e32 v151, s52, v176
	ds_read_b128 v[164:167], v151
	ds_read_b128 v[168:171], v151 offset:1024
	ds_read_b128 v[172:175], v151 offset:2048
	ds_read_b128 v[180:183], v151 offset:3072
	v_lshl_add_u64 v[216:217], s[0:1], 0, v[146:147]
	s_add_i32 m0, s37, 0xc000
	ds_read_b128 v[184:187], v178
	ds_read_b128 v[188:191], v178 offset:1024
	ds_read_b128 v[192:195], v178 offset:2048
	ds_read_b128 v[196:199], v178 offset:3072
	ds_read_b128 v[200:203], v178 offset:4096
	ds_read_b128 v[204:207], v178 offset:5120
	ds_read_b128 v[208:211], v178 offset:6144
	ds_read_b128 v[212:215], v178 offset:7168
	global_load_lds_dwordx4 v[216:217], off
	v_lshl_add_u64 v[216:217], s[0:1], 0, v[148:149]
	s_add_i32 m0, s37, 0xe000
	s_nop 0
	global_load_lds_dwordx4 v[216:217], off
	s_waitcnt vmcnt(8)
	s_waitcnt lgkmcnt(0)
	s_barrier
	s_setprio 1
	s_waitcnt lgkmcnt(0)
	s_nop 0
	v_mfma_f32_16x16x32_bf16 v[128:131], v[132:135], v[184:187], v[128:131]
	v_mfma_f32_16x16x32_bf16 v[124:127], v[156:159], v[184:187], v[124:127]
	v_mfma_f32_16x16x32_bf16 v[112:115], v[132:135], v[192:195], v[112:115]
	v_mfma_f32_16x16x32_bf16 v[108:111], v[156:159], v[192:195], v[108:111]
	v_mfma_f32_16x16x32_bf16 v[96:99], v[132:135], v[200:203], v[96:99]
	v_mfma_f32_16x16x32_bf16 v[92:95], v[156:159], v[200:203], v[92:95]
	v_mfma_f32_16x16x32_bf16 v[80:83], v[132:135], v[208:211], v[80:83]
	v_mfma_f32_16x16x32_bf16 v[76:79], v[156:159], v[208:211], v[76:79]
	v_mfma_f32_16x16x32_bf16 v[128:131], v[152:155], v[188:191], v[128:131]
	v_mfma_f32_16x16x32_bf16 v[124:127], v[160:163], v[188:191], v[124:127]
	v_mfma_f32_16x16x32_bf16 v[112:115], v[152:155], v[196:199], v[112:115]
	v_mfma_f32_16x16x32_bf16 v[108:111], v[160:163], v[196:199], v[108:111]
	v_mfma_f32_16x16x32_bf16 v[96:99], v[152:155], v[204:207], v[96:99]
	v_mfma_f32_16x16x32_bf16 v[92:95], v[160:163], v[204:207], v[92:95]
	v_mfma_f32_16x16x32_bf16 v[80:83], v[152:155], v[212:215], v[80:83]
	v_mfma_f32_16x16x32_bf16 v[76:79], v[160:163], v[212:215], v[76:79]
	s_setprio 0
	s_setprio 1
	v_mfma_f32_16x16x32_bf16 v[120:123], v[164:167], v[184:187], v[120:123]
	v_mfma_f32_16x16x32_bf16 v[116:119], v[172:175], v[184:187], v[116:119]
	v_mfma_f32_16x16x32_bf16 v[104:107], v[164:167], v[192:195], v[104:107]
	v_mfma_f32_16x16x32_bf16 v[100:103], v[172:175], v[192:195], v[100:103]
	v_mfma_f32_16x16x32_bf16 v[88:91], v[164:167], v[200:203], v[88:91]
	v_mfma_f32_16x16x32_bf16 v[84:87], v[172:175], v[200:203], v[84:87]
	v_mfma_f32_16x16x32_bf16 v[72:75], v[164:167], v[208:211], v[72:75]
	v_mfma_f32_16x16x32_bf16 v[68:71], v[172:175], v[208:211], v[68:71]
	v_mfma_f32_16x16x32_bf16 v[120:123], v[168:171], v[188:191], v[120:123]
	v_mfma_f32_16x16x32_bf16 v[116:119], v[180:183], v[188:191], v[116:119]
	v_mfma_f32_16x16x32_bf16 v[104:107], v[168:171], v[196:199], v[104:107]
	v_mfma_f32_16x16x32_bf16 v[100:103], v[180:183], v[196:199], v[100:103]
	v_mfma_f32_16x16x32_bf16 v[88:91], v[168:171], v[204:207], v[88:91]
	v_mfma_f32_16x16x32_bf16 v[84:87], v[180:183], v[204:207], v[84:87]
	v_mfma_f32_16x16x32_bf16 v[72:75], v[168:171], v[212:215], v[72:75]
	v_mfma_f32_16x16x32_bf16 v[68:71], v[180:183], v[212:215], v[68:71]
	s_setprio 0
	s_barrier
	s_add_i32 s50, s50, s36
	v_lshl_add_u64 v[216:217], s[6:7], 0, v[138:139]
	s_mov_b32 m0, s50
	ds_read_b128 v[184:187], v178 offset:16384
	ds_read_b128 v[188:191], v178 offset:17408
	ds_read_b128 v[192:195], v178 offset:18432
	ds_read_b128 v[196:199], v178 offset:19456
	ds_read_b128 v[200:203], v178 offset:20480
	ds_read_b128 v[204:207], v178 offset:21504
	ds_read_b128 v[208:211], v178 offset:22528
	ds_read_b128 v[212:215], v178 offset:23552
	global_load_lds_dwordx4 v[216:217], off
	s_add_i32 m0, s50, 0x2000
	s_add_u32 s50, s6, 0x40000
	v_lshl_add_u64 v[218:219], s[6:7], 0, v[0:1]
	s_addc_u32 s51, s7, 0
	s_add_i32 s52, s52, s36
	global_load_lds_dwordx4 v[218:219], off
	v_lshl_add_u64 v[220:221], s[50:51], 0, v[138:139]
	s_mov_b32 m0, s52
	v_lshl_add_u64 v[224:225], s[8:9], 0, v[136:137]
	global_load_lds_dwordx4 v[220:221], off
	v_lshl_add_u64 v[220:221], s[50:51], 0, v[0:1]
	s_add_i32 m0, s52, 0x2000
	s_nop 0
	global_load_lds_dwordx4 v[220:221], off
	v_lshl_add_u64 v[220:221], s[8:9], 0, v[140:141]
	s_waitcnt vmcnt(6)
	s_waitcnt lgkmcnt(0)
	s_barrier
	s_setprio 1
	s_waitcnt lgkmcnt(0)
	s_nop 0
	v_mfma_f32_16x16x32_bf16 v[64:67], v[132:135], v[184:187], v[64:67]
	v_mfma_f32_16x16x32_bf16 v[60:63], v[156:159], v[184:187], v[60:63]
	v_mfma_f32_16x16x32_bf16 v[48:51], v[132:135], v[192:195], v[48:51]
	v_mfma_f32_16x16x32_bf16 v[44:47], v[156:159], v[192:195], v[44:47]
	v_mfma_f32_16x16x32_bf16 v[32:35], v[132:135], v[200:203], v[32:35]
	v_mfma_f32_16x16x32_bf16 v[28:31], v[156:159], v[200:203], v[28:31]
	v_mfma_f32_16x16x32_bf16 v[16:19], v[132:135], v[208:211], v[16:19]
	v_mfma_f32_16x16x32_bf16 v[12:15], v[156:159], v[208:211], v[12:15]
	v_mfma_f32_16x16x32_bf16 v[64:67], v[152:155], v[188:191], v[64:67]
	v_mfma_f32_16x16x32_bf16 v[60:63], v[160:163], v[188:191], v[60:63]
	v_mfma_f32_16x16x32_bf16 v[48:51], v[152:155], v[196:199], v[48:51]
	v_mfma_f32_16x16x32_bf16 v[44:47], v[160:163], v[196:199], v[44:47]
	v_mfma_f32_16x16x32_bf16 v[32:35], v[152:155], v[204:207], v[32:35]
	v_mfma_f32_16x16x32_bf16 v[28:31], v[160:163], v[204:207], v[28:31]
	v_mfma_f32_16x16x32_bf16 v[16:19], v[152:155], v[212:215], v[16:19]
	v_mfma_f32_16x16x32_bf16 v[12:15], v[160:163], v[212:215], v[12:15]
	s_setprio 0
	s_setprio 1
	v_mfma_f32_16x16x32_bf16 v[56:59], v[164:167], v[184:187], v[56:59]
	v_mfma_f32_16x16x32_bf16 v[52:55], v[172:175], v[184:187], v[52:55]
	v_mfma_f32_16x16x32_bf16 v[40:43], v[164:167], v[192:195], v[40:43]
	v_mfma_f32_16x16x32_bf16 v[36:39], v[172:175], v[192:195], v[36:39]
	v_mfma_f32_16x16x32_bf16 v[24:27], v[164:167], v[200:203], v[24:27]
	v_mfma_f32_16x16x32_bf16 v[20:23], v[172:175], v[200:203], v[20:23]
	v_mfma_f32_16x16x32_bf16 v[8:11], v[164:167], v[208:211], v[8:11]
	v_mfma_f32_16x16x32_bf16 v[4:7], v[172:175], v[208:211], v[4:7]
	v_mfma_f32_16x16x32_bf16 v[56:59], v[168:171], v[188:191], v[56:59]
	v_mfma_f32_16x16x32_bf16 v[52:55], v[180:183], v[188:191], v[52:55]
	v_mfma_f32_16x16x32_bf16 v[40:43], v[168:171], v[196:199], v[40:43]
	v_mfma_f32_16x16x32_bf16 v[36:39], v[180:183], v[196:199], v[36:39]
	v_mfma_f32_16x16x32_bf16 v[24:27], v[168:171], v[204:207], v[24:27]
	v_mfma_f32_16x16x32_bf16 v[20:23], v[180:183], v[204:207], v[20:23]
	v_mfma_f32_16x16x32_bf16 v[8:11], v[168:171], v[212:215], v[8:11]
	v_mfma_f32_16x16x32_bf16 v[4:7], v[180:183], v[212:215], v[4:7]
	s_setprio 0
	s_barrier
.Lb1_ph3:
	s_add_i32 s50, 16, 0x18000
	v_add_u32_e32 v151, s50, v176
	s_add_i32 s51, 16, 0x1c000
	ds_read_b128 v[132:135], v151
	ds_read_b128 v[152:155], v151 offset:1024
	ds_read_b128 v[156:159], v151 offset:2048
	ds_read_b128 v[160:163], v151 offset:3072
	v_add_u32_e32 v151, s51, v176
	ds_read_b128 v[164:167], v151
	ds_read_b128 v[168:171], v151 offset:1024
	ds_read_b128 v[172:175], v151 offset:2048
	ds_read_b128 v[180:183], v151 offset:3072
	s_mov_b32 m0, s37
	s_nop 0
	global_load_lds_dwordx4 v[220:221], off
	s_mov_b32 m0, s38
	s_nop 0
	global_load_lds_dwordx4 v[224:225], off
	s_add_u32 s8, s8, 0x40000
	s_addc_u32 s9, s9, 0
	s_mov_b32 m0, s39
	v_lshl_add_u64 v[226:227], s[8:9], 0, v[140:141]
	ds_read_b128 v[184:187], v178 offset:32768
	ds_read_b128 v[188:191], v178 offset:33792
	ds_read_b128 v[192:195], v178 offset:34816
	ds_read_b128 v[196:199], v178 offset:35840
	ds_read_b128 v[200:203], v178 offset:36864
	ds_read_b128 v[204:207], v178 offset:37888
	ds_read_b128 v[208:211], v178 offset:38912
	ds_read_b128 v[212:215], v178 offset:39936
	global_load_lds_dwordx4 v[226:227], off
	v_lshl_add_u64 v[226:227], s[8:9], 0, v[136:137]
	s_mov_b32 m0, s40
	s_nop 0
	global_load_lds_dwordx4 v[226:227], off
	s_waitcnt vmcnt(8)
	s_waitcnt lgkmcnt(0)
	s_barrier
	s_setprio 1
	s_waitcnt lgkmcnt(0)
	s_nop 0
	v_mfma_f32_16x16x32_bf16 v[128:131], v[132:135], v[184:187], v[128:131]
	v_mfma_f32_16x16x32_bf16 v[124:127], v[156:159], v[184:187], v[124:127]
	v_mfma_f32_16x16x32_bf16 v[112:115], v[132:135], v[192:195], v[112:115]
	v_mfma_f32_16x16x32_bf16 v[108:111], v[156:159], v[192:195], v[108:111]
	v_mfma_f32_16x16x32_bf16 v[96:99], v[132:135], v[200:203], v[96:99]
	v_mfma_f32_16x16x32_bf16 v[92:95], v[156:159], v[200:203], v[92:95]
	v_mfma_f32_16x16x32_bf16 v[80:83], v[132:135], v[208:211], v[80:83]
	v_mfma_f32_16x16x32_bf16 v[76:79], v[156:159], v[208:211], v[76:79]
	v_mfma_f32_16x16x32_bf16 v[128:131], v[152:155], v[188:191], v[128:131]
	v_mfma_f32_16x16x32_bf16 v[124:127], v[160:163], v[188:191], v[124:127]
	v_mfma_f32_16x16x32_bf16 v[112:115], v[152:155], v[196:199], v[112:115]
	v_mfma_f32_16x16x32_bf16 v[108:111], v[160:163], v[196:199], v[108:111]
	v_mfma_f32_16x16x32_bf16 v[96:99], v[152:155], v[204:207], v[96:99]
	v_mfma_f32_16x16x32_bf16 v[92:95], v[160:163], v[204:207], v[92:95]
	v_mfma_f32_16x16x32_bf16 v[80:83], v[152:155], v[212:215], v[80:83]
	v_mfma_f32_16x16x32_bf16 v[76:79], v[160:163], v[212:215], v[76:79]
	s_setprio 0
	s_setprio 1
	v_mfma_f32_16x16x32_bf16 v[120:123], v[164:167], v[184:187], v[120:123]
	v_mfma_f32_16x16x32_bf16 v[116:119], v[172:175], v[184:187], v[116:119]
	v_mfma_f32_16x16x32_bf16 v[104:107], v[164:167], v[192:195], v[104:107]
	v_mfma_f32_16x16x32_bf16 v[100:103], v[172:175], v[192:195], v[100:103]
	v_mfma_f32_16x16x32_bf16 v[88:91], v[164:167], v[200:203], v[88:91]
	v_mfma_f32_16x16x32_bf16 v[84:87], v[172:175], v[200:203], v[84:87]
	v_mfma_f32_16x16x32_bf16 v[72:75], v[164:167], v[208:211], v[72:75]
	v_mfma_f32_16x16x32_bf16 v[68:71], v[172:175], v[208:211], v[68:71]
	v_mfma_f32_16x16x32_bf16 v[120:123], v[168:171], v[188:191], v[120:123]
	v_mfma_f32_16x16x32_bf16 v[116:119], v[180:183], v[188:191], v[116:119]
	v_mfma_f32_16x16x32_bf16 v[104:107], v[168:171], v[196:199], v[104:107]
	v_mfma_f32_16x16x32_bf16 v[100:103], v[180:183], v[196:199], v[100:103]
	v_mfma_f32_16x16x32_bf16 v[88:91], v[168:171], v[204:207], v[88:91]
	v_mfma_f32_16x16x32_bf16 v[84:87], v[180:183], v[204:207], v[84:87]
	v_mfma_f32_16x16x32_bf16 v[72:75], v[168:171], v[212:215], v[72:75]
	v_mfma_f32_16x16x32_bf16 v[68:71], v[180:183], v[212:215], v[68:71]
	s_setprio 0
	s_barrier
	s_add_i32 s8, s50, s36
	v_lshl_add_u64 v[216:217], v[216:217], 0, s[84:85]
	s_mov_b32 m0, s8
	ds_read_b128 v[184:187], v178 offset:49152
	ds_read_b128 v[188:191], v178 offset:50176
	ds_read_b128 v[192:195], v178 offset:51200
	ds_read_b128 v[196:199], v178 offset:52224
	ds_read_b128 v[200:203], v178 offset:53248
	ds_read_b128 v[204:207], v178 offset:54272
	ds_read_b128 v[208:211], v178 offset:55296
	ds_read_b128 v[212:215], v178 offset:56320
	global_load_lds_dwordx4 v[216:217], off
	s_add_i32 m0, s8, 0x2000
	s_add_u32 s6, s6, 0x40080
	v_lshl_add_u64 v[216:217], v[218:219], 0, s[84:85]
	s_addc_u32 s7, s7, 0
	s_add_i32 s8, s51, s36
	global_load_lds_dwordx4 v[216:217], off
	v_lshl_add_u64 v[216:217], s[6:7], 0, v[138:139]
	s_mov_b32 m0, s8
	s_nop 0
	global_load_lds_dwordx4 v[216:217], off
	v_lshl_add_u64 v[216:217], s[6:7], 0, v[0:1]
	s_add_i32 m0, s8, 0x2000
	s_nop 0
	global_load_lds_dwordx4 v[216:217], off
	v_lshl_add_u64 v[216:217], v[220:221], 0, s[84:85]
	s_mov_b32 m0, s44
	s_nop 0
	global_load_lds_dwordx4 v[216:217], off
	v_lshl_add_u64 v[216:217], v[224:225], 0, s[84:85]
	s_mov_b32 m0, s45
	s_nop 0
	global_load_lds_dwordx4 v[216:217], off
	s_waitcnt vmcnt(8)
	s_waitcnt lgkmcnt(0)
	s_barrier
	s_setprio 1
	s_waitcnt lgkmcnt(0)
	v_mfma_f32_16x16x32_bf16 v[64:67], v[132:135], v[184:187], v[64:67]
	v_mfma_f32_16x16x32_bf16 v[60:63], v[156:159], v[184:187], v[60:63]
	v_mfma_f32_16x16x32_bf16 v[48:51], v[132:135], v[192:195], v[48:51]
	v_mfma_f32_16x16x32_bf16 v[44:47], v[156:159], v[192:195], v[44:47]
	v_mfma_f32_16x16x32_bf16 v[32:35], v[132:135], v[200:203], v[32:35]
	v_mfma_f32_16x16x32_bf16 v[28:31], v[156:159], v[200:203], v[28:31]
	v_mfma_f32_16x16x32_bf16 v[16:19], v[132:135], v[208:211], v[16:19]
	v_mfma_f32_16x16x32_bf16 v[12:15], v[156:159], v[208:211], v[12:15]
	v_mfma_f32_16x16x32_bf16 v[64:67], v[152:155], v[188:191], v[64:67]
	v_mfma_f32_16x16x32_bf16 v[60:63], v[160:163], v[188:191], v[60:63]
	v_mfma_f32_16x16x32_bf16 v[48:51], v[152:155], v[196:199], v[48:51]
	v_mfma_f32_16x16x32_bf16 v[44:47], v[160:163], v[196:199], v[44:47]
	v_mfma_f32_16x16x32_bf16 v[32:35], v[152:155], v[204:207], v[32:35]
	v_mfma_f32_16x16x32_bf16 v[28:31], v[160:163], v[204:207], v[28:31]
	v_mfma_f32_16x16x32_bf16 v[16:19], v[152:155], v[212:215], v[16:19]
	v_mfma_f32_16x16x32_bf16 v[12:15], v[160:163], v[212:215], v[12:15]
	s_setprio 0
	s_setprio 1
	v_mfma_f32_16x16x32_bf16 v[56:59], v[164:167], v[184:187], v[56:59]
	v_mfma_f32_16x16x32_bf16 v[52:55], v[172:175], v[184:187], v[52:55]
	v_mfma_f32_16x16x32_bf16 v[40:43], v[164:167], v[192:195], v[40:43]
	v_mfma_f32_16x16x32_bf16 v[36:39], v[172:175], v[192:195], v[36:39]
	v_mfma_f32_16x16x32_bf16 v[24:27], v[164:167], v[200:203], v[24:27]
	v_mfma_f32_16x16x32_bf16 v[20:23], v[172:175], v[200:203], v[20:23]
	v_mfma_f32_16x16x32_bf16 v[8:11], v[164:167], v[208:211], v[8:11]
	v_mfma_f32_16x16x32_bf16 v[4:7], v[172:175], v[208:211], v[4:7]
	v_mfma_f32_16x16x32_bf16 v[56:59], v[168:171], v[188:191], v[56:59]
	v_mfma_f32_16x16x32_bf16 v[52:55], v[180:183], v[188:191], v[52:55]
	v_mfma_f32_16x16x32_bf16 v[40:43], v[168:171], v[196:199], v[40:43]
	v_mfma_f32_16x16x32_bf16 v[36:39], v[180:183], v[196:199], v[36:39]
	v_mfma_f32_16x16x32_bf16 v[24:27], v[168:171], v[204:207], v[24:27]
	v_mfma_f32_16x16x32_bf16 v[20:23], v[180:183], v[204:207], v[20:23]
	v_mfma_f32_16x16x32_bf16 v[8:11], v[168:171], v[212:215], v[8:11]
	v_mfma_f32_16x16x32_bf16 v[4:7], v[180:183], v[212:215], v[4:7]
	s_setprio 0
	s_barrier
	s_add_i32 s49, s49, 2
	s_add_u32 s0, s0, 0x100
	s_addc_u32 s1, s1, 0
	s_add_u32 s29, s29, 0x100
	s_addc_u32 s42, s42, 0
	s_cmp_gt_u32 s49, 13
	s_cbranch_scc0 .LBB0_156
	s_and_b64 vcc, exec, s[18:19]
	s_cbranch_vccz .LBB0_159
	s_barrier

.LBB0_445:
	s_ashr_i32 s23, s22, 31
	s_lshl_b64 s[24:25], s[22:23], 19
	s_add_u32 s24, s34, s24
	s_addc_u32 s25, s35, s25
	s_and_b64 s[26:27], s[6:7], exec
	s_cselect_b32 s3, s25, s1
	s_cselect_b32 s23, s24, s0
	s_ashr_i32 s21, s20, 31
	s_lshl_b64 s[26:27], s[20:21], 19
	s_add_u32 s26, s36, s26
	s_addc_u32 s27, s37, s27
	s_and_b64 s[30:31], s[6:7], exec
	s_cselect_b32 s21, s27, s29
	s_cselect_b32 s48, s26, s28
	s_add_u32 s0, s0, 0x40080
	s_addc_u32 s1, s1, 0
	s_add_u32 s49, s28, 0x100
	s_addc_u32 s50, s29, 0
	s_mov_b32 s51, -2
	s_waitcnt vmcnt(0)
	s_add_u32 s28, s0, 0xfffc0080
	s_addc_u32 s29, s1, -1
	s_add_i32 s52, 16, 0x10000
	s_cmp_eq_u32 s51, 12
	s_cselect_b32 s31, s3, s29
	s_cselect_b32 s30, s23, s28
	v_add_u32_e32 v3, s52, v175
	s_cselect_b32 s29, s21, s50
	s_cselect_b32 s28, s48, s49
	s_add_i32 s54, 16, 0x14000
	ds_read_b128 v[142:145], v3
	s_waitcnt lgkmcnt(0)
	ds_read_b128 v[146:149], v3 offset:1024
	ds_read_b128 v[150:153], v3 offset:2048
	ds_read_b128 v[154:157], v3 offset:3072
	v_add_u32_e32 v3, s54, v175
	ds_read_b128 v[158:161], v3
	ds_read_b128 v[162:165], v3 offset:1024
	ds_read_b128 v[166:169], v3 offset:2048
	ds_read_b128 v[170:173], v3 offset:3072
	v_lshl_add_u64 v[210:211], s[0:1], 0, v[138:139]
	s_add_i32 m0, s39, 0xc000
	ds_read_b128 v[178:181], v177
	ds_read_b128 v[182:185], v177 offset:1024
	ds_read_b128 v[186:189], v177 offset:2048
	ds_read_b128 v[190:193], v177 offset:3072
	ds_read_b128 v[194:197], v177 offset:4096
	ds_read_b128 v[198:201], v177 offset:5120
	ds_read_b128 v[202:205], v177 offset:6144
	ds_read_b128 v[206:209], v177 offset:7168
	global_load_lds_dwordx4 v[210:211], off
	v_lshl_add_u64 v[210:211], s[0:1], 0, v[140:141]
	s_add_i32 m0, s39, 0xe000
	s_nop 0
	global_load_lds_dwordx4 v[210:211], off
	s_waitcnt vmcnt(8)
	s_waitcnt lgkmcnt(0)
	s_barrier
	s_setprio 1
	s_waitcnt lgkmcnt(0)
	v_mfma_f32_16x16x32_bf16 v[128:131], v[142:145], v[178:181], 0
	v_mfma_f32_16x16x32_bf16 v[120:123], v[150:153], v[178:181], 0
	v_mfma_f32_16x16x32_bf16 v[112:115], v[142:145], v[186:189], 0
	v_mfma_f32_16x16x32_bf16 v[104:107], v[150:153], v[186:189], 0
	v_mfma_f32_16x16x32_bf16 v[96:99], v[142:145], v[194:197], 0
	v_mfma_f32_16x16x32_bf16 v[88:91], v[150:153], v[194:197], 0
	v_mfma_f32_16x16x32_bf16 v[80:83], v[142:145], v[202:205], 0
	v_mfma_f32_16x16x32_bf16 v[72:75], v[150:153], v[202:205], 0
	v_mfma_f32_16x16x32_bf16 v[128:131], v[146:149], v[182:185], v[128:131]
	v_mfma_f32_16x16x32_bf16 v[120:123], v[154:157], v[182:185], v[120:123]
	v_mfma_f32_16x16x32_bf16 v[112:115], v[146:149], v[190:193], v[112:115]
	v_mfma_f32_16x16x32_bf16 v[104:107], v[154:157], v[190:193], v[104:107]
	v_mfma_f32_16x16x32_bf16 v[96:99], v[146:149], v[198:201], v[96:99]
	v_mfma_f32_16x16x32_bf16 v[88:91], v[154:157], v[198:201], v[88:91]
	v_mfma_f32_16x16x32_bf16 v[80:83], v[146:149], v[206:209], v[80:83]
	v_mfma_f32_16x16x32_bf16 v[72:75], v[154:157], v[206:209], v[72:75]
	s_setprio 0
	s_setprio 1
	v_mfma_f32_16x16x32_bf16 v[124:127], v[158:161], v[178:181], 0
	v_mfma_f32_16x16x32_bf16 v[116:119], v[166:169], v[178:181], 0
	v_mfma_f32_16x16x32_bf16 v[108:111], v[158:161], v[186:189], 0
	v_mfma_f32_16x16x32_bf16 v[100:103], v[166:169], v[186:189], 0
	v_mfma_f32_16x16x32_bf16 v[92:95], v[158:161], v[194:197], 0
	v_mfma_f32_16x16x32_bf16 v[84:87], v[166:169], v[194:197], 0
	v_mfma_f32_16x16x32_bf16 v[76:79], v[158:161], v[202:205], 0
	v_mfma_f32_16x16x32_bf16 v[68:71], v[166:169], v[202:205], 0
	v_mfma_f32_16x16x32_bf16 v[124:127], v[162:165], v[182:185], v[124:127]
	v_mfma_f32_16x16x32_bf16 v[116:119], v[170:173], v[182:185], v[116:119]
	v_mfma_f32_16x16x32_bf16 v[108:111], v[162:165], v[190:193], v[108:111]
	v_mfma_f32_16x16x32_bf16 v[100:103], v[170:173], v[190:193], v[100:103]
	v_mfma_f32_16x16x32_bf16 v[92:95], v[162:165], v[198:201], v[92:95]
	v_mfma_f32_16x16x32_bf16 v[84:87], v[170:173], v[198:201], v[84:87]
	v_mfma_f32_16x16x32_bf16 v[76:79], v[162:165], v[206:209], v[76:79]
	v_mfma_f32_16x16x32_bf16 v[68:71], v[170:173], v[206:209], v[68:71]
	s_setprio 0
	s_barrier
	s_add_i32 s52, s52, s38
	v_lshl_add_u64 v[210:211], s[28:29], 0, v[134:135]
	s_mov_b32 m0, s52
	ds_read_b128 v[178:181], v177 offset:16384
	ds_read_b128 v[182:185], v177 offset:17408
	ds_read_b128 v[186:189], v177 offset:18432
	ds_read_b128 v[190:193], v177 offset:19456
	ds_read_b128 v[194:197], v177 offset:20480
	ds_read_b128 v[198:201], v177 offset:21504
	ds_read_b128 v[202:205], v177 offset:22528
	ds_read_b128 v[206:209], v177 offset:23552
	global_load_lds_dwordx4 v[210:211], off
	s_add_i32 m0, s52, 0x2000
	s_add_u32 s52, s28, 0x40000
	v_lshl_add_u64 v[212:213], s[28:29], 0, v[0:1]
	s_addc_u32 s53, s29, 0
	s_add_i32 s54, s54, s38
	global_load_lds_dwordx4 v[212:213], off
	v_lshl_add_u64 v[214:215], s[52:53], 0, v[134:135]
	s_mov_b32 m0, s54
	v_lshl_add_u64 v[216:217], s[30:31], 0, v[132:133]
	global_load_lds_dwordx4 v[214:215], off
	v_lshl_add_u64 v[214:215], s[52:53], 0, v[0:1]
	s_add_i32 m0, s54, 0x2000
	s_nop 0
	global_load_lds_dwordx4 v[214:215], off
	v_lshl_add_u64 v[214:215], s[30:31], 0, v[136:137]
	s_waitcnt vmcnt(6)
	s_waitcnt lgkmcnt(0)
	s_barrier
	s_setprio 1
	s_waitcnt lgkmcnt(0)
	s_nop 0
	v_mfma_f32_16x16x32_bf16 v[64:67], v[142:145], v[178:181], 0
	v_mfma_f32_16x16x32_bf16 v[56:59], v[150:153], v[178:181], 0
	v_mfma_f32_16x16x32_bf16 v[48:51], v[142:145], v[186:189], 0
	v_mfma_f32_16x16x32_bf16 v[40:43], v[150:153], v[186:189], 0
	v_mfma_f32_16x16x32_bf16 v[32:35], v[142:145], v[194:197], 0
	v_mfma_f32_16x16x32_bf16 v[24:27], v[150:153], v[194:197], 0
	v_mfma_f32_16x16x32_bf16 v[16:19], v[142:145], v[202:205], 0
	v_mfma_f32_16x16x32_bf16 v[8:11], v[150:153], v[202:205], 0
	v_mfma_f32_16x16x32_bf16 v[64:67], v[146:149], v[182:185], v[64:67]
	v_mfma_f32_16x16x32_bf16 v[56:59], v[154:157], v[182:185], v[56:59]
	v_mfma_f32_16x16x32_bf16 v[48:51], v[146:149], v[190:193], v[48:51]
	v_mfma_f32_16x16x32_bf16 v[40:43], v[154:157], v[190:193], v[40:43]
	v_mfma_f32_16x16x32_bf16 v[32:35], v[146:149], v[198:201], v[32:35]
	v_mfma_f32_16x16x32_bf16 v[24:27], v[154:157], v[198:201], v[24:27]
	v_mfma_f32_16x16x32_bf16 v[16:19], v[146:149], v[206:209], v[16:19]
	v_mfma_f32_16x16x32_bf16 v[8:11], v[154:157], v[206:209], v[8:11]
	s_setprio 0
	s_setprio 1
	v_mfma_f32_16x16x32_bf16 v[60:63], v[158:161], v[178:181], 0
	v_mfma_f32_16x16x32_bf16 v[52:55], v[166:169], v[178:181], 0
	v_mfma_f32_16x16x32_bf16 v[44:47], v[158:161], v[186:189], 0
	v_mfma_f32_16x16x32_bf16 v[36:39], v[166:169], v[186:189], 0
	v_mfma_f32_16x16x32_bf16 v[28:31], v[158:161], v[194:197], 0
	v_mfma_f32_16x16x32_bf16 v[20:23], v[166:169], v[194:197], 0
	v_mfma_f32_16x16x32_bf16 v[12:15], v[158:161], v[202:205], 0
	v_mfma_f32_16x16x32_bf16 v[4:7], v[166:169], v[202:205], 0
	v_mfma_f32_16x16x32_bf16 v[60:63], v[162:165], v[182:185], v[60:63]
	v_mfma_f32_16x16x32_bf16 v[52:55], v[170:173], v[182:185], v[52:55]
	v_mfma_f32_16x16x32_bf16 v[44:47], v[162:165], v[190:193], v[44:47]
	v_mfma_f32_16x16x32_bf16 v[36:39], v[170:173], v[190:193], v[36:39]
	v_mfma_f32_16x16x32_bf16 v[28:31], v[162:165], v[198:201], v[28:31]
	v_mfma_f32_16x16x32_bf16 v[20:23], v[170:173], v[198:201], v[20:23]
	v_mfma_f32_16x16x32_bf16 v[12:15], v[162:165], v[206:209], v[12:15]
	v_mfma_f32_16x16x32_bf16 v[4:7], v[170:173], v[206:209], v[4:7]
	s_setprio 0
	s_barrier
	s_branch .La1_ph3
.LBB0_446:
	s_add_u32 s28, s0, 0xfffc0080
	s_addc_u32 s29, s1, -1
	s_add_i32 s52, 16, 0x10000
	s_cmp_eq_u32 s51, 12
	s_cselect_b32 s31, s3, s29
	s_cselect_b32 s30, s23, s28
	v_add_u32_e32 v3, s52, v175
	s_cselect_b32 s29, s21, s50
	s_cselect_b32 s28, s48, s49
	s_add_i32 s54, 16, 0x14000
	ds_read_b128 v[142:145], v3
	s_waitcnt lgkmcnt(0)
	ds_read_b128 v[146:149], v3 offset:1024
	ds_read_b128 v[150:153], v3 offset:2048
	ds_read_b128 v[154:157], v3 offset:3072
	v_add_u32_e32 v3, s54, v175
	ds_read_b128 v[158:161], v3
	ds_read_b128 v[162:165], v3 offset:1024
	ds_read_b128 v[166:169], v3 offset:2048
	ds_read_b128 v[170:173], v3 offset:3072
	v_lshl_add_u64 v[210:211], s[0:1], 0, v[138:139]
	s_add_i32 m0, s39, 0xc000
	ds_read_b128 v[178:181], v177
	ds_read_b128 v[182:185], v177 offset:1024
	ds_read_b128 v[186:189], v177 offset:2048
	ds_read_b128 v[190:193], v177 offset:3072
	ds_read_b128 v[194:197], v177 offset:4096
	ds_read_b128 v[198:201], v177 offset:5120
	ds_read_b128 v[202:205], v177 offset:6144
	ds_read_b128 v[206:209], v177 offset:7168
	global_load_lds_dwordx4 v[210:211], off
	v_lshl_add_u64 v[210:211], s[0:1], 0, v[140:141]
	s_add_i32 m0, s39, 0xe000
	s_nop 0
	global_load_lds_dwordx4 v[210:211], off
	s_waitcnt vmcnt(8)
	s_waitcnt lgkmcnt(0)
	s_barrier
	s_setprio 1
	s_waitcnt lgkmcnt(0)
	v_mfma_f32_16x16x32_bf16 v[128:131], v[142:145], v[178:181], v[128:131]
	v_mfma_f32_16x16x32_bf16 v[120:123], v[150:153], v[178:181], v[120:123]
	v_mfma_f32_16x16x32_bf16 v[112:115], v[142:145], v[186:189], v[112:115]
	v_mfma_f32_16x16x32_bf16 v[104:107], v[150:153], v[186:189], v[104:107]
	v_mfma_f32_16x16x32_bf16 v[96:99], v[142:145], v[194:197], v[96:99]
	v_mfma_f32_16x16x32_bf16 v[88:91], v[150:153], v[194:197], v[88:91]
	v_mfma_f32_16x16x32_bf16 v[80:83], v[142:145], v[202:205], v[80:83]
	v_mfma_f32_16x16x32_bf16 v[72:75], v[150:153], v[202:205], v[72:75]
	v_mfma_f32_16x16x32_bf16 v[128:131], v[146:149], v[182:185], v[128:131]
	v_mfma_f32_16x16x32_bf16 v[120:123], v[154:157], v[182:185], v[120:123]
	v_mfma_f32_16x16x32_bf16 v[112:115], v[146:149], v[190:193], v[112:115]
	v_mfma_f32_16x16x32_bf16 v[104:107], v[154:157], v[190:193], v[104:107]
	v_mfma_f32_16x16x32_bf16 v[96:99], v[146:149], v[198:201], v[96:99]
	v_mfma_f32_16x16x32_bf16 v[88:91], v[154:157], v[198:201], v[88:91]
	v_mfma_f32_16x16x32_bf16 v[80:83], v[146:149], v[206:209], v[80:83]
	v_mfma_f32_16x16x32_bf16 v[72:75], v[154:157], v[206:209], v[72:75]
	s_setprio 0
	s_setprio 1
	v_mfma_f32_16x16x32_bf16 v[124:127], v[158:161], v[178:181], v[124:127]
	v_mfma_f32_16x16x32_bf16 v[116:119], v[166:169], v[178:181], v[116:119]
	v_mfma_f32_16x16x32_bf16 v[108:111], v[158:161], v[186:189], v[108:111]
	v_mfma_f32_16x16x32_bf16 v[100:103], v[166:169], v[186:189], v[100:103]
	v_mfma_f32_16x16x32_bf16 v[92:95], v[158:161], v[194:197], v[92:95]
	v_mfma_f32_16x16x32_bf16 v[84:87], v[166:169], v[194:197], v[84:87]
	v_mfma_f32_16x16x32_bf16 v[76:79], v[158:161], v[202:205], v[76:79]
	v_mfma_f32_16x16x32_bf16 v[68:71], v[166:169], v[202:205], v[68:71]
	v_mfma_f32_16x16x32_bf16 v[124:127], v[162:165], v[182:185], v[124:127]
	v_mfma_f32_16x16x32_bf16 v[116:119], v[170:173], v[182:185], v[116:119]
	v_mfma_f32_16x16x32_bf16 v[108:111], v[162:165], v[190:193], v[108:111]
	v_mfma_f32_16x16x32_bf16 v[100:103], v[170:173], v[190:193], v[100:103]
	v_mfma_f32_16x16x32_bf16 v[92:95], v[162:165], v[198:201], v[92:95]
	v_mfma_f32_16x16x32_bf16 v[84:87], v[170:173], v[198:201], v[84:87]
	v_mfma_f32_16x16x32_bf16 v[76:79], v[162:165], v[206:209], v[76:79]
	v_mfma_f32_16x16x32_bf16 v[68:71], v[170:173], v[206:209], v[68:71]
	s_setprio 0
	s_barrier
	s_add_i32 s52, s52, s38
	v_lshl_add_u64 v[210:211], s[28:29], 0, v[134:135]
	s_mov_b32 m0, s52
	ds_read_b128 v[178:181], v177 offset:16384
	ds_read_b128 v[182:185], v177 offset:17408
	ds_read_b128 v[186:189], v177 offset:18432
	ds_read_b128 v[190:193], v177 offset:19456
	ds_read_b128 v[194:197], v177 offset:20480
	ds_read_b128 v[198:201], v177 offset:21504
	ds_read_b128 v[202:205], v177 offset:22528
	ds_read_b128 v[206:209], v177 offset:23552
	global_load_lds_dwordx4 v[210:211], off
	s_add_i32 m0, s52, 0x2000
	s_add_u32 s52, s28, 0x40000
	v_lshl_add_u64 v[212:213], s[28:29], 0, v[0:1]
	s_addc_u32 s53, s29, 0
	s_add_i32 s54, s54, s38
	global_load_lds_dwordx4 v[212:213], off
	v_lshl_add_u64 v[214:215], s[52:53], 0, v[134:135]
	s_mov_b32 m0, s54
	v_lshl_add_u64 v[216:217], s[30:31], 0, v[132:133]
	global_load_lds_dwordx4 v[214:215], off
	v_lshl_add_u64 v[214:215], s[52:53], 0, v[0:1]
	s_add_i32 m0, s54, 0x2000
	s_nop 0
	global_load_lds_dwordx4 v[214:215], off
	v_lshl_add_u64 v[214:215], s[30:31], 0, v[136:137]
	s_waitcnt vmcnt(6)
	s_waitcnt lgkmcnt(0)
	s_barrier
	s_setprio 1
	s_waitcnt lgkmcnt(0)
	s_nop 0
	v_mfma_f32_16x16x32_bf16 v[64:67], v[142:145], v[178:181], v[64:67]
	v_mfma_f32_16x16x32_bf16 v[56:59], v[150:153], v[178:181], v[56:59]
	v_mfma_f32_16x16x32_bf16 v[48:51], v[142:145], v[186:189], v[48:51]
	v_mfma_f32_16x16x32_bf16 v[40:43], v[150:153], v[186:189], v[40:43]
	v_mfma_f32_16x16x32_bf16 v[32:35], v[142:145], v[194:197], v[32:35]
	v_mfma_f32_16x16x32_bf16 v[24:27], v[150:153], v[194:197], v[24:27]
	v_mfma_f32_16x16x32_bf16 v[16:19], v[142:145], v[202:205], v[16:19]
	v_mfma_f32_16x16x32_bf16 v[8:11], v[150:153], v[202:205], v[8:11]
	v_mfma_f32_16x16x32_bf16 v[64:67], v[146:149], v[182:185], v[64:67]
	v_mfma_f32_16x16x32_bf16 v[56:59], v[154:157], v[182:185], v[56:59]
	v_mfma_f32_16x16x32_bf16 v[48:51], v[146:149], v[190:193], v[48:51]
	v_mfma_f32_16x16x32_bf16 v[40:43], v[154:157], v[190:193], v[40:43]
	v_mfma_f32_16x16x32_bf16 v[32:35], v[146:149], v[198:201], v[32:35]
	v_mfma_f32_16x16x32_bf16 v[24:27], v[154:157], v[198:201], v[24:27]
	v_mfma_f32_16x16x32_bf16 v[16:19], v[146:149], v[206:209], v[16:19]
	v_mfma_f32_16x16x32_bf16 v[8:11], v[154:157], v[206:209], v[8:11]
	s_setprio 0
	s_setprio 1
	v_mfma_f32_16x16x32_bf16 v[60:63], v[158:161], v[178:181], v[60:63]
	v_mfma_f32_16x16x32_bf16 v[52:55], v[166:169], v[178:181], v[52:55]
	v_mfma_f32_16x16x32_bf16 v[44:47], v[158:161], v[186:189], v[44:47]
	v_mfma_f32_16x16x32_bf16 v[36:39], v[166:169], v[186:189], v[36:39]
	v_mfma_f32_16x16x32_bf16 v[28:31], v[158:161], v[194:197], v[28:31]
	v_mfma_f32_16x16x32_bf16 v[20:23], v[166:169], v[194:197], v[20:23]
	v_mfma_f32_16x16x32_bf16 v[12:15], v[158:161], v[202:205], v[12:15]
	v_mfma_f32_16x16x32_bf16 v[4:7], v[166:169], v[202:205], v[4:7]
	v_mfma_f32_16x16x32_bf16 v[60:63], v[162:165], v[182:185], v[60:63]
	v_mfma_f32_16x16x32_bf16 v[52:55], v[170:173], v[182:185], v[52:55]
	v_mfma_f32_16x16x32_bf16 v[44:47], v[162:165], v[190:193], v[44:47]
	v_mfma_f32_16x16x32_bf16 v[36:39], v[170:173], v[190:193], v[36:39]
	v_mfma_f32_16x16x32_bf16 v[28:31], v[162:165], v[198:201], v[28:31]
	v_mfma_f32_16x16x32_bf16 v[20:23], v[170:173], v[198:201], v[20:23]
	v_mfma_f32_16x16x32_bf16 v[12:15], v[162:165], v[206:209], v[12:15]
	v_mfma_f32_16x16x32_bf16 v[4:7], v[170:173], v[206:209], v[4:7]
	s_setprio 0
	s_barrier
.La1_ph3:
	s_add_i32 s52, 16, 0x18000
	v_add_u32_e32 v3, s52, v175
	s_add_i32 s53, 16, 0x1c000
	ds_read_b128 v[142:145], v3
	ds_read_b128 v[146:149], v3 offset:1024
	ds_read_b128 v[150:153], v3 offset:2048
	ds_read_b128 v[154:157], v3 offset:3072
	v_add_u32_e32 v3, s53, v175
	ds_read_b128 v[158:161], v3
	ds_read_b128 v[162:165], v3 offset:1024
	ds_read_b128 v[166:169], v3 offset:2048
	ds_read_b128 v[170:173], v3 offset:3072
	s_mov_b32 m0, s39
	s_nop 0
	global_load_lds_dwordx4 v[214:215], off
	s_mov_b32 m0, s40
	s_nop 0
	global_load_lds_dwordx4 v[216:217], off
	s_add_u32 s30, s30, 0x40000
	s_addc_u32 s31, s31, 0
	s_mov_b32 m0, s41
	v_lshl_add_u64 v[218:219], s[30:31], 0, v[136:137]
	ds_read_b128 v[178:181], v177 offset:32768
	ds_read_b128 v[182:185], v177 offset:33792
	ds_read_b128 v[186:189], v177 offset:34816
	ds_read_b128 v[190:193], v177 offset:35840
	ds_read_b128 v[194:197], v177 offset:36864
	ds_read_b128 v[198:201], v177 offset:37888
	ds_read_b128 v[202:205], v177 offset:38912
	ds_read_b128 v[206:209], v177 offset:39936
	global_load_lds_dwordx4 v[218:219], off
	v_lshl_add_u64 v[218:219], s[30:31], 0, v[132:133]
	s_mov_b32 m0, s42
	s_nop 0
	global_load_lds_dwordx4 v[218:219], off
	s_waitcnt vmcnt(8)
	s_waitcnt lgkmcnt(0)
	s_barrier
	s_setprio 1
	s_waitcnt lgkmcnt(0)
	s_nop 0
	v_mfma_f32_16x16x32_bf16 v[128:131], v[142:145], v[178:181], v[128:131]
	v_mfma_f32_16x16x32_bf16 v[120:123], v[150:153], v[178:181], v[120:123]
	v_mfma_f32_16x16x32_bf16 v[112:115], v[142:145], v[186:189], v[112:115]
	v_mfma_f32_16x16x32_bf16 v[104:107], v[150:153], v[186:189], v[104:107]
	v_mfma_f32_16x16x32_bf16 v[96:99], v[142:145], v[194:197], v[96:99]
	v_mfma_f32_16x16x32_bf16 v[88:91], v[150:153], v[194:197], v[88:91]
	v_mfma_f32_16x16x32_bf16 v[80:83], v[142:145], v[202:205], v[80:83]
	v_mfma_f32_16x16x32_bf16 v[72:75], v[150:153], v[202:205], v[72:75]
	v_mfma_f32_16x16x32_bf16 v[128:131], v[146:149], v[182:185], v[128:131]
	v_mfma_f32_16x16x32_bf16 v[120:123], v[154:157], v[182:185], v[120:123]
	v_mfma_f32_16x16x32_bf16 v[112:115], v[146:149], v[190:193], v[112:115]
	v_mfma_f32_16x16x32_bf16 v[104:107], v[154:157], v[190:193], v[104:107]
	v_mfma_f32_16x16x32_bf16 v[96:99], v[146:149], v[198:201], v[96:99]
	v_mfma_f32_16x16x32_bf16 v[88:91], v[154:157], v[198:201], v[88:91]
	v_mfma_f32_16x16x32_bf16 v[80:83], v[146:149], v[206:209], v[80:83]
	v_mfma_f32_16x16x32_bf16 v[72:75], v[154:157], v[206:209], v[72:75]
	s_setprio 0
	s_setprio 1
	v_mfma_f32_16x16x32_bf16 v[124:127], v[158:161], v[178:181], v[124:127]
	v_mfma_f32_16x16x32_bf16 v[116:119], v[166:169], v[178:181], v[116:119]
	v_mfma_f32_16x16x32_bf16 v[108:111], v[158:161], v[186:189], v[108:111]
	v_mfma_f32_16x16x32_bf16 v[100:103], v[166:169], v[186:189], v[100:103]
	v_mfma_f32_16x16x32_bf16 v[92:95], v[158:161], v[194:197], v[92:95]
	v_mfma_f32_16x16x32_bf16 v[84:87], v[166:169], v[194:197], v[84:87]
	v_mfma_f32_16x16x32_bf16 v[76:79], v[158:161], v[202:205], v[76:79]
	v_mfma_f32_16x16x32_bf16 v[68:71], v[166:169], v[202:205], v[68:71]
	v_mfma_f32_16x16x32_bf16 v[124:127], v[162:165], v[182:185], v[124:127]
	v_mfma_f32_16x16x32_bf16 v[116:119], v[170:173], v[182:185], v[116:119]
	v_mfma_f32_16x16x32_bf16 v[108:111], v[162:165], v[190:193], v[108:111]
	v_mfma_f32_16x16x32_bf16 v[100:103], v[170:173], v[190:193], v[100:103]
	v_mfma_f32_16x16x32_bf16 v[92:95], v[162:165], v[198:201], v[92:95]
	v_mfma_f32_16x16x32_bf16 v[84:87], v[170:173], v[198:201], v[84:87]
	v_mfma_f32_16x16x32_bf16 v[76:79], v[162:165], v[206:209], v[76:79]
	v_mfma_f32_16x16x32_bf16 v[68:71], v[170:173], v[206:209], v[68:71]
	s_setprio 0
	s_barrier
	s_add_i32 s30, s52, s38
	v_lshl_add_u64 v[210:211], v[210:211], 0, s[84:85]
	s_mov_b32 m0, s30
	ds_read_b128 v[178:181], v177 offset:49152
	ds_read_b128 v[182:185], v177 offset:50176
	ds_read_b128 v[186:189], v177 offset:51200
	ds_read_b128 v[190:193], v177 offset:52224
	ds_read_b128 v[194:197], v177 offset:53248
	ds_read_b128 v[198:201], v177 offset:54272
	ds_read_b128 v[202:205], v177 offset:55296
	ds_read_b128 v[206:209], v177 offset:56320
	global_load_lds_dwordx4 v[210:211], off
	s_add_i32 m0, s30, 0x2000
	s_add_u32 s28, s28, 0x40080
	v_lshl_add_u64 v[210:211], v[212:213], 0, s[84:85]
	s_addc_u32 s29, s29, 0
	s_add_i32 s30, s53, s38
	global_load_lds_dwordx4 v[210:211], off
	v_lshl_add_u64 v[210:211], s[28:29], 0, v[134:135]
	s_mov_b32 m0, s30
	s_nop 0
	global_load_lds_dwordx4 v[210:211], off
	v_lshl_add_u64 v[210:211], s[28:29], 0, v[0:1]
	s_add_i32 m0, s30, 0x2000
	s_nop 0
	global_load_lds_dwordx4 v[210:211], off
	v_lshl_add_u64 v[210:211], v[214:215], 0, s[84:85]
	s_mov_b32 m0, s44
	s_nop 0
	global_load_lds_dwordx4 v[210:211], off
	v_lshl_add_u64 v[210:211], v[216:217], 0, s[84:85]
	s_mov_b32 m0, s45
	s_nop 0
	global_load_lds_dwordx4 v[210:211], off
	s_waitcnt vmcnt(8)
	s_waitcnt lgkmcnt(0)
	s_barrier
	s_setprio 1
	s_waitcnt lgkmcnt(0)
	v_mfma_f32_16x16x32_bf16 v[64:67], v[142:145], v[178:181], v[64:67]
	v_mfma_f32_16x16x32_bf16 v[56:59], v[150:153], v[178:181], v[56:59]
	v_mfma_f32_16x16x32_bf16 v[48:51], v[142:145], v[186:189], v[48:51]
	v_mfma_f32_16x16x32_bf16 v[40:43], v[150:153], v[186:189], v[40:43]
	v_mfma_f32_16x16x32_bf16 v[32:35], v[142:145], v[194:197], v[32:35]
	v_mfma_f32_16x16x32_bf16 v[24:27], v[150:153], v[194:197], v[24:27]
	v_mfma_f32_16x16x32_bf16 v[16:19], v[142:145], v[202:205], v[16:19]
	v_mfma_f32_16x16x32_bf16 v[8:11], v[150:153], v[202:205], v[8:11]
	v_mfma_f32_16x16x32_bf16 v[64:67], v[146:149], v[182:185], v[64:67]
	v_mfma_f32_16x16x32_bf16 v[56:59], v[154:157], v[182:185], v[56:59]
	v_mfma_f32_16x16x32_bf16 v[48:51], v[146:149], v[190:193], v[48:51]
	v_mfma_f32_16x16x32_bf16 v[40:43], v[154:157], v[190:193], v[40:43]
	v_mfma_f32_16x16x32_bf16 v[32:35], v[146:149], v[198:201], v[32:35]
	v_mfma_f32_16x16x32_bf16 v[24:27], v[154:157], v[198:201], v[24:27]
	v_mfma_f32_16x16x32_bf16 v[16:19], v[146:149], v[206:209], v[16:19]
	v_mfma_f32_16x16x32_bf16 v[8:11], v[154:157], v[206:209], v[8:11]
	s_setprio 0
	s_setprio 1
	v_mfma_f32_16x16x32_bf16 v[60:63], v[158:161], v[178:181], v[60:63]
	v_mfma_f32_16x16x32_bf16 v[52:55], v[166:169], v[178:181], v[52:55]
	v_mfma_f32_16x16x32_bf16 v[44:47], v[158:161], v[186:189], v[44:47]
	v_mfma_f32_16x16x32_bf16 v[36:39], v[166:169], v[186:189], v[36:39]
	v_mfma_f32_16x16x32_bf16 v[28:31], v[158:161], v[194:197], v[28:31]
	v_mfma_f32_16x16x32_bf16 v[20:23], v[166:169], v[194:197], v[20:23]
	v_mfma_f32_16x16x32_bf16 v[12:15], v[158:161], v[202:205], v[12:15]
	v_mfma_f32_16x16x32_bf16 v[4:7], v[166:169], v[202:205], v[4:7]
	v_mfma_f32_16x16x32_bf16 v[60:63], v[162:165], v[182:185], v[60:63]
	v_mfma_f32_16x16x32_bf16 v[52:55], v[170:173], v[182:185], v[52:55]
	v_mfma_f32_16x16x32_bf16 v[44:47], v[162:165], v[190:193], v[44:47]
	v_mfma_f32_16x16x32_bf16 v[36:39], v[170:173], v[190:193], v[36:39]
	v_mfma_f32_16x16x32_bf16 v[28:31], v[162:165], v[198:201], v[28:31]
	v_mfma_f32_16x16x32_bf16 v[20:23], v[170:173], v[198:201], v[20:23]
	v_mfma_f32_16x16x32_bf16 v[12:15], v[162:165], v[206:209], v[12:15]
	v_mfma_f32_16x16x32_bf16 v[4:7], v[170:173], v[206:209], v[4:7]
	s_setprio 0
	s_barrier
	s_add_i32 s51, s51, 2
	s_add_u32 s0, s0, 0x100
	s_addc_u32 s1, s1, 0
	s_add_u32 s49, s49, 0x100
	s_addc_u32 s50, s50, 0
	s_cmp_gt_u32 s51, 13
	s_cbranch_scc0 .LBB0_446
	s_and_b64 vcc, exec, s[18:19]
	s_cbranch_vccz .LBB0_449
	s_barrier

.LBB0_620:
	s_add_i32 s58, s34, 2
	s_add_u32 s59, s22, s30
	s_addc_u32 s35, s23, s31
	s_add_u32 s60, s0, s30
	s_addc_u32 s61, s1, s31
	s_add_i32 s62, 16, 0x10000
	s_cmp_eq_u32 s54, s34
	s_cselect_b32 s35, s9, s35
	s_cselect_b32 s34, s8, s59
	v_add_u32_e32 v149, s62, v147
	s_cselect_b32 s61, s29, s61
	s_cselect_b32 s60, s28, s60
	s_add_i32 s59, 16, 0x14000
	ds_read_b128 v[150:153], v149
	ds_read_b128 v[154:157], v149 offset:1024
	ds_read_b128 v[158:161], v149 offset:2048
	ds_read_b128 v[162:165], v149 offset:3072
	v_add_u32_e32 v149, s59, v147
	ds_read_b128 v[166:169], v149
	ds_read_b128 v[170:173], v149 offset:1024
	ds_read_b128 v[174:177], v149 offset:2048
	ds_read_b128 v[178:181], v149 offset:3072
	v_lshl_add_u64 v[214:215], s[22:23], 0, v[144:145]
	s_add_i32 m0, s47, 0xc000
	ds_read_b128 v[182:185], v148
	ds_read_b128 v[186:189], v148 offset:1024
	ds_read_b128 v[190:193], v148 offset:2048
	ds_read_b128 v[194:197], v148 offset:3072
	ds_read_b128 v[198:201], v148 offset:4096
	ds_read_b128 v[202:205], v148 offset:5120
	ds_read_b128 v[206:209], v148 offset:6144
	ds_read_b128 v[210:213], v148 offset:7168
	global_load_lds_dwordx4 v[214:215], off
	v_lshl_add_u64 v[214:215], s[22:23], 0, v[142:143]
	s_add_i32 m0, s47, 0xe000
	s_nop 0
	global_load_lds_dwordx4 v[214:215], off
	s_waitcnt vmcnt(8)
	s_waitcnt lgkmcnt(0)
	s_barrier
	s_setprio 1
	s_waitcnt lgkmcnt(0)
	v_mfma_f32_16x16x32_bf16 v[128:131], v[150:153], v[182:185], v[128:131]
	v_mfma_f32_16x16x32_bf16 v[124:127], v[158:161], v[182:185], v[124:127]
	v_mfma_f32_16x16x32_bf16 v[120:123], v[150:153], v[190:193], v[120:123]
	v_mfma_f32_16x16x32_bf16 v[116:119], v[158:161], v[190:193], v[116:119]
	v_mfma_f32_16x16x32_bf16 v[112:115], v[150:153], v[198:201], v[112:115]
	v_mfma_f32_16x16x32_bf16 v[108:111], v[158:161], v[198:201], v[108:111]
	v_mfma_f32_16x16x32_bf16 v[104:107], v[150:153], v[206:209], v[104:107]
	v_mfma_f32_16x16x32_bf16 v[100:103], v[158:161], v[206:209], v[100:103]
	v_mfma_f32_16x16x32_bf16 v[128:131], v[154:157], v[186:189], v[128:131]
	v_mfma_f32_16x16x32_bf16 v[124:127], v[162:165], v[186:189], v[124:127]
	v_mfma_f32_16x16x32_bf16 v[120:123], v[154:157], v[194:197], v[120:123]
	v_mfma_f32_16x16x32_bf16 v[116:119], v[162:165], v[194:197], v[116:119]
	v_mfma_f32_16x16x32_bf16 v[112:115], v[154:157], v[202:205], v[112:115]
	v_mfma_f32_16x16x32_bf16 v[108:111], v[162:165], v[202:205], v[108:111]
	v_mfma_f32_16x16x32_bf16 v[104:107], v[154:157], v[210:213], v[104:107]
	v_mfma_f32_16x16x32_bf16 v[100:103], v[162:165], v[210:213], v[100:103]
	s_setprio 0
	s_setprio 1
	v_mfma_f32_16x16x32_bf16 v[64:67], v[166:169], v[182:185], v[64:67]
	v_mfma_f32_16x16x32_bf16 v[60:63], v[174:177], v[182:185], v[60:63]
	v_mfma_f32_16x16x32_bf16 v[56:59], v[166:169], v[190:193], v[56:59]
	v_mfma_f32_16x16x32_bf16 v[52:55], v[174:177], v[190:193], v[52:55]
	v_mfma_f32_16x16x32_bf16 v[48:51], v[166:169], v[198:201], v[48:51]
	v_mfma_f32_16x16x32_bf16 v[44:47], v[174:177], v[198:201], v[44:47]
	v_mfma_f32_16x16x32_bf16 v[40:43], v[166:169], v[206:209], v[40:43]
	v_mfma_f32_16x16x32_bf16 v[36:39], v[174:177], v[206:209], v[36:39]
	v_mfma_f32_16x16x32_bf16 v[64:67], v[170:173], v[186:189], v[64:67]
	v_mfma_f32_16x16x32_bf16 v[60:63], v[178:181], v[186:189], v[60:63]
	v_mfma_f32_16x16x32_bf16 v[56:59], v[170:173], v[194:197], v[56:59]
	v_mfma_f32_16x16x32_bf16 v[52:55], v[178:181], v[194:197], v[52:55]
	v_mfma_f32_16x16x32_bf16 v[48:51], v[170:173], v[202:205], v[48:51]
	v_mfma_f32_16x16x32_bf16 v[44:47], v[178:181], v[202:205], v[44:47]
	v_mfma_f32_16x16x32_bf16 v[40:43], v[170:173], v[210:213], v[40:43]
	v_mfma_f32_16x16x32_bf16 v[36:39], v[178:181], v[210:213], v[36:39]
	s_setprio 0
	s_barrier
	s_add_i32 s62, s62, s42
	v_lshl_add_u64 v[214:215], s[60:61], 0, v[134:135]
	s_mov_b32 m0, s62
	ds_read_b128 v[182:185], v148 offset:16384
	ds_read_b128 v[186:189], v148 offset:17408
	ds_read_b128 v[190:193], v148 offset:18432
	ds_read_b128 v[194:197], v148 offset:19456
	ds_read_b128 v[198:201], v148 offset:20480
	ds_read_b128 v[202:205], v148 offset:21504
	ds_read_b128 v[206:209], v148 offset:22528
	ds_read_b128 v[210:213], v148 offset:23552
	global_load_lds_dwordx4 v[214:215], off
	s_add_i32 m0, s62, 0x2000
	v_lshl_add_u64 v[216:217], s[60:61], 0, v[0:1]
	s_add_u32 s60, s60, s40
	s_addc_u32 s61, s61, 0
	s_add_i32 s59, s59, s42
	global_load_lds_dwordx4 v[216:217], off
	v_lshl_add_u64 v[218:219], s[60:61], 0, v[134:135]
	s_mov_b32 m0, s59
	v_lshl_add_u64 v[220:221], s[60:61], 0, v[0:1]
	global_load_lds_dwordx4 v[218:219], off
	s_add_i32 m0, s59, 0x2000
	v_lshl_add_u64 v[224:225], s[34:35], 0, v[136:137]
	global_load_lds_dwordx4 v[220:221], off
	v_lshl_add_u64 v[226:227], s[34:35], 0, v[132:133]
	s_waitcnt vmcnt(6)
	s_waitcnt lgkmcnt(0)
	s_barrier
	s_setprio 1
	s_waitcnt lgkmcnt(0)
	s_nop 0
	v_mfma_f32_16x16x32_bf16 v[96:99], v[150:153], v[182:185], v[96:99]
	v_mfma_f32_16x16x32_bf16 v[92:95], v[158:161], v[182:185], v[92:95]
	v_mfma_f32_16x16x32_bf16 v[88:91], v[150:153], v[190:193], v[88:91]
	v_mfma_f32_16x16x32_bf16 v[84:87], v[158:161], v[190:193], v[84:87]
	v_mfma_f32_16x16x32_bf16 v[80:83], v[150:153], v[198:201], v[80:83]
	v_mfma_f32_16x16x32_bf16 v[76:79], v[158:161], v[198:201], v[76:79]
	v_mfma_f32_16x16x32_bf16 v[72:75], v[150:153], v[206:209], v[72:75]
	v_mfma_f32_16x16x32_bf16 v[68:71], v[158:161], v[206:209], v[68:71]
	v_mfma_f32_16x16x32_bf16 v[96:99], v[154:157], v[186:189], v[96:99]
	v_mfma_f32_16x16x32_bf16 v[92:95], v[162:165], v[186:189], v[92:95]
	v_mfma_f32_16x16x32_bf16 v[88:91], v[154:157], v[194:197], v[88:91]
	v_mfma_f32_16x16x32_bf16 v[84:87], v[162:165], v[194:197], v[84:87]
	v_mfma_f32_16x16x32_bf16 v[80:83], v[154:157], v[202:205], v[80:83]
	v_mfma_f32_16x16x32_bf16 v[76:79], v[162:165], v[202:205], v[76:79]
	v_mfma_f32_16x16x32_bf16 v[72:75], v[154:157], v[210:213], v[72:75]
	v_mfma_f32_16x16x32_bf16 v[68:71], v[162:165], v[210:213], v[68:71]
	s_setprio 0
	s_setprio 1
	v_mfma_f32_16x16x32_bf16 v[32:35], v[166:169], v[182:185], v[32:35]
	v_mfma_f32_16x16x32_bf16 v[28:31], v[174:177], v[182:185], v[28:31]
	v_mfma_f32_16x16x32_bf16 v[24:27], v[166:169], v[190:193], v[24:27]
	v_mfma_f32_16x16x32_bf16 v[20:23], v[174:177], v[190:193], v[20:23]
	v_mfma_f32_16x16x32_bf16 v[16:19], v[166:169], v[198:201], v[16:19]
	v_mfma_f32_16x16x32_bf16 v[12:15], v[174:177], v[198:201], v[12:15]
	v_mfma_f32_16x16x32_bf16 v[8:11], v[166:169], v[206:209], v[8:11]
	v_mfma_f32_16x16x32_bf16 v[4:7], v[174:177], v[206:209], v[4:7]
	v_mfma_f32_16x16x32_bf16 v[32:35], v[170:173], v[186:189], v[32:35]
	v_mfma_f32_16x16x32_bf16 v[28:31], v[178:181], v[186:189], v[28:31]
	v_mfma_f32_16x16x32_bf16 v[24:27], v[170:173], v[194:197], v[24:27]
	v_mfma_f32_16x16x32_bf16 v[20:23], v[178:181], v[194:197], v[20:23]
	v_mfma_f32_16x16x32_bf16 v[16:19], v[170:173], v[202:205], v[16:19]
	v_mfma_f32_16x16x32_bf16 v[12:15], v[178:181], v[202:205], v[12:15]
	v_mfma_f32_16x16x32_bf16 v[8:11], v[170:173], v[210:213], v[8:11]
	v_mfma_f32_16x16x32_bf16 v[4:7], v[178:181], v[210:213], v[4:7]
	s_setprio 0
	s_barrier
	s_add_i32 s59, 16, 0x18000
	v_add_u32_e32 v149, s59, v147
	s_add_i32 s60, 16, 0x1c000
	ds_read_b128 v[150:153], v149
	ds_read_b128 v[154:157], v149 offset:1024
	ds_read_b128 v[158:161], v149 offset:2048
	ds_read_b128 v[162:165], v149 offset:3072
	v_add_u32_e32 v149, s60, v147
	ds_read_b128 v[166:169], v149
	ds_read_b128 v[170:173], v149 offset:1024
	ds_read_b128 v[174:177], v149 offset:2048
	ds_read_b128 v[178:181], v149 offset:3072
	s_mov_b32 m0, s47
	s_nop 0
	global_load_lds_dwordx4 v[224:225], off
	s_mov_b32 m0, s48
	s_nop 0
	global_load_lds_dwordx4 v[226:227], off
	s_add_u32 s34, s34, s40
	s_addc_u32 s35, s35, 0
	s_mov_b32 m0, s49
	v_lshl_add_u64 v[228:229], s[34:35], 0, v[136:137]
	ds_read_b128 v[182:185], v148 offset:32768
	ds_read_b128 v[186:189], v148 offset:33792
	ds_read_b128 v[190:193], v148 offset:34816
	ds_read_b128 v[194:197], v148 offset:35840
	ds_read_b128 v[198:201], v148 offset:36864
	ds_read_b128 v[202:205], v148 offset:37888
	ds_read_b128 v[206:209], v148 offset:38912
	ds_read_b128 v[210:213], v148 offset:39936
	global_load_lds_dwordx4 v[228:229], off
	v_lshl_add_u64 v[228:229], s[34:35], 0, v[132:133]
	s_mov_b32 m0, s50
	s_nop 0
	global_load_lds_dwordx4 v[228:229], off
	s_waitcnt vmcnt(8)
	s_waitcnt lgkmcnt(0)
	s_barrier
	s_setprio 1
	s_waitcnt lgkmcnt(0)
	v_mfma_f32_16x16x32_bf16 v[128:131], v[150:153], v[182:185], v[128:131]
	v_mfma_f32_16x16x32_bf16 v[124:127], v[158:161], v[182:185], v[124:127]
	v_mfma_f32_16x16x32_bf16 v[120:123], v[150:153], v[190:193], v[120:123]
	v_mfma_f32_16x16x32_bf16 v[116:119], v[158:161], v[190:193], v[116:119]
	v_mfma_f32_16x16x32_bf16 v[112:115], v[150:153], v[198:201], v[112:115]
	v_mfma_f32_16x16x32_bf16 v[108:111], v[158:161], v[198:201], v[108:111]
	v_mfma_f32_16x16x32_bf16 v[104:107], v[150:153], v[206:209], v[104:107]
	v_mfma_f32_16x16x32_bf16 v[100:103], v[158:161], v[206:209], v[100:103]
	v_mfma_f32_16x16x32_bf16 v[128:131], v[154:157], v[186:189], v[128:131]
	v_mfma_f32_16x16x32_bf16 v[124:127], v[162:165], v[186:189], v[124:127]
	v_mfma_f32_16x16x32_bf16 v[120:123], v[154:157], v[194:197], v[120:123]
	v_mfma_f32_16x16x32_bf16 v[116:119], v[162:165], v[194:197], v[116:119]
	v_mfma_f32_16x16x32_bf16 v[112:115], v[154:157], v[202:205], v[112:115]
	v_mfma_f32_16x16x32_bf16 v[108:111], v[162:165], v[202:205], v[108:111]
	v_mfma_f32_16x16x32_bf16 v[104:107], v[154:157], v[210:213], v[104:107]
	v_mfma_f32_16x16x32_bf16 v[100:103], v[162:165], v[210:213], v[100:103]
	s_setprio 0
	s_setprio 1
	v_mfma_f32_16x16x32_bf16 v[64:67], v[166:169], v[182:185], v[64:67]
	v_mfma_f32_16x16x32_bf16 v[60:63], v[174:177], v[182:185], v[60:63]
	v_mfma_f32_16x16x32_bf16 v[56:59], v[166:169], v[190:193], v[56:59]
	v_mfma_f32_16x16x32_bf16 v[52:55], v[174:177], v[190:193], v[52:55]
	v_mfma_f32_16x16x32_bf16 v[48:51], v[166:169], v[198:201], v[48:51]
	v_mfma_f32_16x16x32_bf16 v[44:47], v[174:177], v[198:201], v[44:47]
	v_mfma_f32_16x16x32_bf16 v[40:43], v[166:169], v[206:209], v[40:43]
	v_mfma_f32_16x16x32_bf16 v[36:39], v[174:177], v[206:209], v[36:39]
	v_mfma_f32_16x16x32_bf16 v[64:67], v[170:173], v[186:189], v[64:67]
	v_mfma_f32_16x16x32_bf16 v[60:63], v[178:181], v[186:189], v[60:63]
	v_mfma_f32_16x16x32_bf16 v[56:59], v[170:173], v[194:197], v[56:59]
	v_mfma_f32_16x16x32_bf16 v[52:55], v[178:181], v[194:197], v[52:55]
	v_mfma_f32_16x16x32_bf16 v[48:51], v[170:173], v[202:205], v[48:51]
	v_mfma_f32_16x16x32_bf16 v[44:47], v[178:181], v[202:205], v[44:47]
	v_mfma_f32_16x16x32_bf16 v[40:43], v[170:173], v[210:213], v[40:43]
	v_mfma_f32_16x16x32_bf16 v[36:39], v[178:181], v[210:213], v[36:39]
	s_setprio 0
	s_barrier
	s_add_i32 s34, s59, s42
	v_lshl_add_u64 v[214:215], v[214:215], 0, s[84:85]
	s_mov_b32 m0, s34
	ds_read_b128 v[182:185], v148 offset:49152
	ds_read_b128 v[186:189], v148 offset:50176
	ds_read_b128 v[190:193], v148 offset:51200
	ds_read_b128 v[194:197], v148 offset:52224
	ds_read_b128 v[198:201], v148 offset:53248
	ds_read_b128 v[202:205], v148 offset:54272
	ds_read_b128 v[206:209], v148 offset:55296
	ds_read_b128 v[210:213], v148 offset:56320
	global_load_lds_dwordx4 v[214:215], off
	v_lshl_add_u64 v[214:215], v[216:217], 0, s[84:85]
	s_add_i32 m0, s34, 0x2000
	s_add_i32 s34, s60, s42
	global_load_lds_dwordx4 v[214:215], off
	v_lshl_add_u64 v[214:215], v[218:219], 0, s[84:85]
	s_mov_b32 m0, s34
	s_nop 0
	global_load_lds_dwordx4 v[214:215], off
	v_lshl_add_u64 v[214:215], v[220:221], 0, s[84:85]
	s_add_i32 m0, s34, 0x2000
	s_nop 0
	global_load_lds_dwordx4 v[214:215], off
	v_lshl_add_u64 v[214:215], v[224:225], 0, s[84:85]
	s_mov_b32 m0, s52
	s_nop 0
	global_load_lds_dwordx4 v[214:215], off
	v_lshl_add_u64 v[214:215], v[226:227], 0, s[84:85]
	s_mov_b32 m0, s53
	s_nop 0
	global_load_lds_dwordx4 v[214:215], off
	s_waitcnt vmcnt(8)
	s_waitcnt lgkmcnt(0)
	s_barrier
	s_setprio 1
	s_waitcnt lgkmcnt(0)
	s_nop 0
	v_mfma_f32_16x16x32_bf16 v[96:99], v[150:153], v[182:185], v[96:99]
	v_mfma_f32_16x16x32_bf16 v[92:95], v[158:161], v[182:185], v[92:95]
	v_mfma_f32_16x16x32_bf16 v[88:91], v[150:153], v[190:193], v[88:91]
	v_mfma_f32_16x16x32_bf16 v[84:87], v[158:161], v[190:193], v[84:87]
	v_mfma_f32_16x16x32_bf16 v[80:83], v[150:153], v[198:201], v[80:83]
	v_mfma_f32_16x16x32_bf16 v[76:79], v[158:161], v[198:201], v[76:79]
	v_mfma_f32_16x16x32_bf16 v[72:75], v[150:153], v[206:209], v[72:75]
	v_mfma_f32_16x16x32_bf16 v[68:71], v[158:161], v[206:209], v[68:71]
	v_mfma_f32_16x16x32_bf16 v[96:99], v[154:157], v[186:189], v[96:99]
	v_mfma_f32_16x16x32_bf16 v[92:95], v[162:165], v[186:189], v[92:95]
	v_mfma_f32_16x16x32_bf16 v[88:91], v[154:157], v[194:197], v[88:91]
	v_mfma_f32_16x16x32_bf16 v[84:87], v[162:165], v[194:197], v[84:87]
	v_mfma_f32_16x16x32_bf16 v[80:83], v[154:157], v[202:205], v[80:83]
	v_mfma_f32_16x16x32_bf16 v[76:79], v[162:165], v[202:205], v[76:79]
	v_mfma_f32_16x16x32_bf16 v[72:75], v[154:157], v[210:213], v[72:75]
	v_mfma_f32_16x16x32_bf16 v[68:71], v[162:165], v[210:213], v[68:71]
	s_setprio 0
	s_setprio 1
	v_mfma_f32_16x16x32_bf16 v[32:35], v[166:169], v[182:185], v[32:35]
	v_mfma_f32_16x16x32_bf16 v[28:31], v[174:177], v[182:185], v[28:31]
	v_mfma_f32_16x16x32_bf16 v[24:27], v[166:169], v[190:193], v[24:27]
	v_mfma_f32_16x16x32_bf16 v[20:23], v[174:177], v[190:193], v[20:23]
	v_mfma_f32_16x16x32_bf16 v[16:19], v[166:169], v[198:201], v[16:19]
	v_mfma_f32_16x16x32_bf16 v[12:15], v[174:177], v[198:201], v[12:15]
	v_mfma_f32_16x16x32_bf16 v[8:11], v[166:169], v[206:209], v[8:11]
	v_mfma_f32_16x16x32_bf16 v[4:7], v[174:177], v[206:209], v[4:7]
	v_mfma_f32_16x16x32_bf16 v[32:35], v[170:173], v[186:189], v[32:35]
	v_mfma_f32_16x16x32_bf16 v[28:31], v[178:181], v[186:189], v[28:31]
	v_mfma_f32_16x16x32_bf16 v[24:27], v[170:173], v[194:197], v[24:27]
	v_mfma_f32_16x16x32_bf16 v[20:23], v[178:181], v[194:197], v[20:23]
	v_mfma_f32_16x16x32_bf16 v[16:19], v[170:173], v[202:205], v[16:19]
	v_mfma_f32_16x16x32_bf16 v[12:15], v[178:181], v[202:205], v[12:15]
	v_mfma_f32_16x16x32_bf16 v[8:11], v[170:173], v[210:213], v[8:11]
	v_mfma_f32_16x16x32_bf16 v[4:7], v[178:181], v[210:213], v[4:7]
	s_setprio 0
	s_barrier
	s_add_u32 s30, s30, 0x100
	s_addc_u32 s31, s31, 0
	v_lshl_add_u64 v[144:145], v[144:145], 0, s[86:87]
	v_lshl_add_u64 v[142:143], v[142:143], 0, s[86:87]
	s_cmp_ge_u32 s58, s51
	s_mov_b32 s34, s58
	s_cbranch_scc0 .LBB0_620
	s_and_b64 vcc, exec, s[26:27]
	s_cbranch_vccnz .LBB0_623
	s_and_b64 vcc, exec, s[6:7]
	s_cbranch_vccnz .LBB0_608
	s_branch .LBB0_624
